# all GEMM K-loops (except GEMM4a): VALU address adds folded into SGPR-base LDS-DMA requests
# speedup vs baseline: 1.0124x; 1.0023x over previous
.LBB0_504:
	ds_read_b128 v[104:107], v200
	ds_read_b128 v[108:111], v200 offset:1024
	ds_read_b128 v[124:127], v200 offset:2048
	ds_read_b128 v[128:131], v200 offset:3072
	ds_read_b128 v[144:147], v201
	ds_read_b128 v[148:151], v201 offset:1024
	ds_read_b128 v[152:155], v201 offset:2048
	ds_read_b128 v[156:159], v201 offset:3072
	s_add_u32 s48, s46, 0xfffc0080
	s_addc_u32 s49, s47, -1
	s_cmp_eq_u32 s87, 12
	s_cselect_b32 s51, s39, s49
	s_cselect_b32 s50, s45, s48
	s_cselect_b32 s49, s37, s86
	s_cselect_b32 s48, s84, s85
	s_add_i32 m0, s52, 0xc000
	ds_read_b128 v[160:163], v202
	ds_read_b128 v[164:167], v202 offset:1024
	ds_read_b128 v[168:171], v202 offset:2048
	ds_read_b128 v[172:175], v202 offset:3072
	ds_read_b128 v[176:179], v202 offset:4096
	ds_read_b128 v[180:183], v202 offset:5120
	ds_read_b128 v[206:209], v202 offset:6144
	ds_read_b128 v[210:213], v202 offset:7168
	global_load_lds_dwordx4 v188, s[46:47]
	s_add_i32 m0, s52, 0xe000
	s_nop 0
	global_load_lds_dwordx4 v190, s[46:47]
	s_waitcnt vmcnt(8)
	s_waitcnt lgkmcnt(0)
	s_setprio 1
	s_barrier
	v_mfma_f32_16x16x32_bf16 v[140:143], v[104:107], v[160:163], v[140:143]
	v_mfma_f32_16x16x32_bf16 v[136:139], v[124:127], v[160:163], v[136:139]
	v_mfma_f32_16x16x32_bf16 v[116:119], v[104:107], v[168:171], v[116:119]
	v_mfma_f32_16x16x32_bf16 v[112:115], v[124:127], v[168:171], v[112:115]
	v_mfma_f32_16x16x32_bf16 v[92:95], v[104:107], v[176:179], v[92:95]
	v_mfma_f32_16x16x32_bf16 v[88:91], v[124:127], v[176:179], v[88:91]
	v_mfma_f32_16x16x32_bf16 v[76:79], v[104:107], v[206:209], v[76:79]
	v_mfma_f32_16x16x32_bf16 v[72:75], v[124:127], v[206:209], v[72:75]
	v_mfma_f32_16x16x32_bf16 v[140:143], v[108:111], v[164:167], v[140:143]
	v_mfma_f32_16x16x32_bf16 v[136:139], v[128:131], v[164:167], v[136:139]
	v_mfma_f32_16x16x32_bf16 v[116:119], v[108:111], v[172:175], v[116:119]
	v_mfma_f32_16x16x32_bf16 v[112:115], v[128:131], v[172:175], v[112:115]
	v_mfma_f32_16x16x32_bf16 v[92:95], v[108:111], v[180:183], v[92:95]
	v_mfma_f32_16x16x32_bf16 v[88:91], v[128:131], v[180:183], v[88:91]
	v_mfma_f32_16x16x32_bf16 v[76:79], v[108:111], v[210:213], v[76:79]
	v_mfma_f32_16x16x32_bf16 v[72:75], v[128:131], v[210:213], v[72:75]
	v_mfma_f32_16x16x32_bf16 v[132:135], v[144:147], v[160:163], v[132:135]
	v_mfma_f32_16x16x32_bf16 v[120:123], v[152:155], v[160:163], v[120:123]
	v_mfma_f32_16x16x32_bf16 v[100:103], v[144:147], v[168:171], v[100:103]
	v_mfma_f32_16x16x32_bf16 v[96:99], v[152:155], v[168:171], v[96:99]
	v_mfma_f32_16x16x32_bf16 v[84:87], v[144:147], v[176:179], v[84:87]
	v_mfma_f32_16x16x32_bf16 v[80:83], v[152:155], v[176:179], v[80:83]
	v_mfma_f32_16x16x32_bf16 v[68:71], v[144:147], v[206:209], v[68:71]
	v_mfma_f32_16x16x32_bf16 v[64:67], v[152:155], v[206:209], v[64:67]
	v_mfma_f32_16x16x32_bf16 v[132:135], v[148:151], v[164:167], v[132:135]
	v_mfma_f32_16x16x32_bf16 v[120:123], v[156:159], v[164:167], v[120:123]
	v_mfma_f32_16x16x32_bf16 v[100:103], v[148:151], v[172:175], v[100:103]
	v_mfma_f32_16x16x32_bf16 v[96:99], v[156:159], v[172:175], v[96:99]
	v_mfma_f32_16x16x32_bf16 v[84:87], v[148:151], v[180:183], v[84:87]
	v_mfma_f32_16x16x32_bf16 v[80:83], v[156:159], v[180:183], v[80:83]
	v_mfma_f32_16x16x32_bf16 v[68:71], v[148:151], v[210:213], v[68:71]
	v_mfma_f32_16x16x32_bf16 v[64:67], v[156:159], v[210:213], v[64:67]
	s_barrier
	s_setprio 0
	s_add_i32 s88, s69, s13
	s_add_u32 s98, s48, 0x80
	s_addc_u32 s99, s49, 0
	s_mov_b32 m0, s88
	ds_read_b128 v[160:163], v202 offset:16384
	ds_read_b128 v[164:167], v202 offset:17408
	ds_read_b128 v[168:171], v202 offset:18432
	ds_read_b128 v[172:175], v202 offset:19456
	ds_read_b128 v[176:179], v202 offset:20480
	ds_read_b128 v[180:183], v202 offset:21504
	ds_read_b128 v[206:209], v202 offset:22528
	ds_read_b128 v[210:213], v202 offset:23552
	global_load_lds_dwordx4 v184, s[48:49]
	s_add_i32 m0, s88, 0x2000
	s_add_u32 s88, s48, 0x40000
	s_addc_u32 s89, s49, 0
	s_add_i32 s90, s70, s13
	global_load_lds_dwordx4 v186, s[48:49]
	s_mov_b32 m0, s90
	s_add_u32 s100, s50, 0x80
	s_addc_u32 s101, s51, 0
	global_load_lds_dwordx4 v184, s[88:89]
	s_add_i32 m0, s90, 0x2000
	s_nop 0
	global_load_lds_dwordx4 v186, s[88:89]
	s_mov_b32 m0, s52
	s_nop 0
	global_load_lds_dwordx4 v184, s[50:51]
	s_mov_b32 m0, s53
	s_nop 0
	global_load_lds_dwordx4 v186, s[50:51]
	s_waitcnt vmcnt(8)
	s_waitcnt lgkmcnt(0)
	s_setprio 1
	s_barrier
	v_mfma_f32_16x16x32_bf16 v[60:63], v[104:107], v[160:163], v[60:63]
	v_mfma_f32_16x16x32_bf16 v[56:59], v[124:127], v[160:163], v[56:59]
	v_mfma_f32_16x16x32_bf16 v[44:47], v[104:107], v[168:171], v[44:47]
	v_mfma_f32_16x16x32_bf16 v[40:43], v[124:127], v[168:171], v[40:43]
	v_mfma_f32_16x16x32_bf16 v[28:31], v[104:107], v[176:179], v[28:31]
	v_mfma_f32_16x16x32_bf16 v[24:27], v[124:127], v[176:179], v[24:27]
	v_mfma_f32_16x16x32_bf16 v[12:15], v[104:107], v[206:209], v[12:15]
	v_mfma_f32_16x16x32_bf16 v[8:11], v[124:127], v[206:209], v[8:11]
	v_mfma_f32_16x16x32_bf16 v[60:63], v[108:111], v[164:167], v[60:63]
	v_mfma_f32_16x16x32_bf16 v[56:59], v[128:131], v[164:167], v[56:59]
	v_mfma_f32_16x16x32_bf16 v[44:47], v[108:111], v[172:175], v[44:47]
	v_mfma_f32_16x16x32_bf16 v[40:43], v[128:131], v[172:175], v[40:43]
	v_mfma_f32_16x16x32_bf16 v[28:31], v[108:111], v[180:183], v[28:31]
	v_mfma_f32_16x16x32_bf16 v[24:27], v[128:131], v[180:183], v[24:27]
	v_mfma_f32_16x16x32_bf16 v[12:15], v[108:111], v[210:213], v[12:15]
	v_mfma_f32_16x16x32_bf16 v[8:11], v[128:131], v[210:213], v[8:11]
	v_mfma_f32_16x16x32_bf16 v[52:55], v[144:147], v[160:163], v[52:55]
	v_mfma_f32_16x16x32_bf16 v[48:51], v[152:155], v[160:163], v[48:51]
	v_mfma_f32_16x16x32_bf16 v[36:39], v[144:147], v[168:171], v[36:39]
	v_mfma_f32_16x16x32_bf16 v[32:35], v[152:155], v[168:171], v[32:35]
	v_mfma_f32_16x16x32_bf16 v[20:23], v[144:147], v[176:179], v[20:23]
	v_mfma_f32_16x16x32_bf16 v[16:19], v[152:155], v[176:179], v[16:19]
	v_mfma_f32_16x16x32_bf16 v[4:7], v[144:147], v[206:209], v[4:7]
	v_mfma_f32_16x16x32_bf16 v[0:3], v[152:155], v[206:209], v[0:3]
	v_mfma_f32_16x16x32_bf16 v[52:55], v[148:151], v[164:167], v[52:55]
	v_mfma_f32_16x16x32_bf16 v[48:51], v[156:159], v[164:167], v[48:51]
	v_mfma_f32_16x16x32_bf16 v[36:39], v[148:151], v[172:175], v[36:39]
	v_mfma_f32_16x16x32_bf16 v[32:35], v[156:159], v[172:175], v[32:35]
	v_mfma_f32_16x16x32_bf16 v[20:23], v[148:151], v[180:183], v[20:23]
	v_mfma_f32_16x16x32_bf16 v[16:19], v[156:159], v[180:183], v[16:19]
	v_mfma_f32_16x16x32_bf16 v[4:7], v[148:151], v[210:213], v[4:7]
	v_mfma_f32_16x16x32_bf16 v[0:3], v[156:159], v[210:213], v[0:3]
	s_barrier
	s_setprio 0
	s_add_i32 s88, 0, 0x18000
	s_add_i32 s89, 0, 0x1c000
	v_add_u32_e32 v128, s88, v199
	v_add_u32_e32 v156, s89, v199
	ds_read_b128 v[104:107], v128
	ds_read_b128 v[108:111], v128 offset:1024
	ds_read_b128 v[124:127], v128 offset:2048
	ds_read_b128 v[128:131], v128 offset:3072
	ds_read_b128 v[144:147], v156
	ds_read_b128 v[148:151], v156 offset:1024
	ds_read_b128 v[152:155], v156 offset:2048
	ds_read_b128 v[156:159], v156 offset:3072
	s_add_u32 s50, s50, 0x40000
	s_addc_u32 s51, s51, 0
	s_mov_b32 m0, s54
	ds_read_b128 v[160:163], v202 offset:32768
	ds_read_b128 v[164:167], v202 offset:33792
	ds_read_b128 v[168:171], v202 offset:34816
	ds_read_b128 v[172:175], v202 offset:35840
	ds_read_b128 v[176:179], v202 offset:36864
	ds_read_b128 v[180:183], v202 offset:37888
	ds_read_b128 v[206:209], v202 offset:38912
	ds_read_b128 v[210:213], v202 offset:39936
	global_load_lds_dwordx4 v184, s[50:51]
	s_mov_b32 m0, s55
	s_nop 0
	global_load_lds_dwordx4 v186, s[50:51]
	s_waitcnt vmcnt(8)
	s_waitcnt lgkmcnt(0)
	s_setprio 1
	s_barrier
	v_mfma_f32_16x16x32_bf16 v[140:143], v[104:107], v[160:163], v[140:143]
	v_mfma_f32_16x16x32_bf16 v[136:139], v[124:127], v[160:163], v[136:139]
	v_mfma_f32_16x16x32_bf16 v[116:119], v[104:107], v[168:171], v[116:119]
	v_mfma_f32_16x16x32_bf16 v[112:115], v[124:127], v[168:171], v[112:115]
	v_mfma_f32_16x16x32_bf16 v[92:95], v[104:107], v[176:179], v[92:95]
	v_mfma_f32_16x16x32_bf16 v[88:91], v[124:127], v[176:179], v[88:91]
	v_mfma_f32_16x16x32_bf16 v[76:79], v[104:107], v[206:209], v[76:79]
	v_mfma_f32_16x16x32_bf16 v[72:75], v[124:127], v[206:209], v[72:75]
	v_mfma_f32_16x16x32_bf16 v[140:143], v[108:111], v[164:167], v[140:143]
	v_mfma_f32_16x16x32_bf16 v[136:139], v[128:131], v[164:167], v[136:139]
	v_mfma_f32_16x16x32_bf16 v[116:119], v[108:111], v[172:175], v[116:119]
	v_mfma_f32_16x16x32_bf16 v[112:115], v[128:131], v[172:175], v[112:115]
	v_mfma_f32_16x16x32_bf16 v[92:95], v[108:111], v[180:183], v[92:95]
	v_mfma_f32_16x16x32_bf16 v[88:91], v[128:131], v[180:183], v[88:91]
	v_mfma_f32_16x16x32_bf16 v[76:79], v[108:111], v[210:213], v[76:79]
	v_mfma_f32_16x16x32_bf16 v[72:75], v[128:131], v[210:213], v[72:75]
	v_mfma_f32_16x16x32_bf16 v[132:135], v[144:147], v[160:163], v[132:135]
	v_mfma_f32_16x16x32_bf16 v[120:123], v[152:155], v[160:163], v[120:123]
	v_mfma_f32_16x16x32_bf16 v[100:103], v[144:147], v[168:171], v[100:103]
	v_mfma_f32_16x16x32_bf16 v[96:99], v[152:155], v[168:171], v[96:99]
	v_mfma_f32_16x16x32_bf16 v[84:87], v[144:147], v[176:179], v[84:87]
	v_mfma_f32_16x16x32_bf16 v[80:83], v[152:155], v[176:179], v[80:83]
	v_mfma_f32_16x16x32_bf16 v[68:71], v[144:147], v[206:209], v[68:71]
	v_mfma_f32_16x16x32_bf16 v[64:67], v[152:155], v[206:209], v[64:67]
	v_mfma_f32_16x16x32_bf16 v[132:135], v[148:151], v[164:167], v[132:135]
	v_mfma_f32_16x16x32_bf16 v[120:123], v[156:159], v[164:167], v[120:123]
	v_mfma_f32_16x16x32_bf16 v[100:103], v[148:151], v[172:175], v[100:103]
	v_mfma_f32_16x16x32_bf16 v[96:99], v[156:159], v[172:175], v[96:99]
	v_mfma_f32_16x16x32_bf16 v[84:87], v[148:151], v[180:183], v[84:87]
	v_mfma_f32_16x16x32_bf16 v[80:83], v[156:159], v[180:183], v[80:83]
	v_mfma_f32_16x16x32_bf16 v[68:71], v[148:151], v[210:213], v[68:71]
	v_mfma_f32_16x16x32_bf16 v[64:67], v[156:159], v[210:213], v[64:67]
	s_barrier
	s_setprio 0
	s_add_i32 s50, s88, s13
	s_mov_b32 m0, s50
	ds_read_b128 v[160:163], v202 offset:49152
	ds_read_b128 v[164:167], v202 offset:50176
	ds_read_b128 v[168:171], v202 offset:51200
	ds_read_b128 v[172:175], v202 offset:52224
	ds_read_b128 v[176:179], v202 offset:53248
	ds_read_b128 v[180:183], v202 offset:54272
	ds_read_b128 v[206:209], v202 offset:55296
	ds_read_b128 v[210:213], v202 offset:56320
	global_load_lds_dwordx4 v184, s[98:99]
	s_add_i32 m0, s50, 0x2000
	s_add_u32 s48, s48, 0x40080
	s_addc_u32 s49, s49, 0
	s_add_i32 s50, s89, s13
	global_load_lds_dwordx4 v186, s[98:99]
	s_mov_b32 m0, s50
	s_nop 0
	global_load_lds_dwordx4 v184, s[48:49]
	s_add_i32 m0, s50, 0x2000
	s_nop 0
	global_load_lds_dwordx4 v186, s[48:49]
	s_mov_b32 m0, s61
	s_nop 0
	global_load_lds_dwordx4 v184, s[100:101]
	s_mov_b32 m0, s62
	s_nop 0
	global_load_lds_dwordx4 v186, s[100:101]
	s_waitcnt vmcnt(8)
	s_waitcnt lgkmcnt(0)
	s_setprio 1
	s_barrier
	v_mfma_f32_16x16x32_bf16 v[60:63], v[104:107], v[160:163], v[60:63]
	v_mfma_f32_16x16x32_bf16 v[56:59], v[124:127], v[160:163], v[56:59]
	v_mfma_f32_16x16x32_bf16 v[44:47], v[104:107], v[168:171], v[44:47]
	v_mfma_f32_16x16x32_bf16 v[40:43], v[124:127], v[168:171], v[40:43]
	v_mfma_f32_16x16x32_bf16 v[28:31], v[104:107], v[176:179], v[28:31]
	v_mfma_f32_16x16x32_bf16 v[24:27], v[124:127], v[176:179], v[24:27]
	v_mfma_f32_16x16x32_bf16 v[12:15], v[104:107], v[206:209], v[12:15]
	v_mfma_f32_16x16x32_bf16 v[8:11], v[124:127], v[206:209], v[8:11]
	v_mfma_f32_16x16x32_bf16 v[60:63], v[108:111], v[164:167], v[60:63]
	v_mfma_f32_16x16x32_bf16 v[56:59], v[128:131], v[164:167], v[56:59]
	v_mfma_f32_16x16x32_bf16 v[44:47], v[108:111], v[172:175], v[44:47]
	v_mfma_f32_16x16x32_bf16 v[40:43], v[128:131], v[172:175], v[40:43]
	v_mfma_f32_16x16x32_bf16 v[28:31], v[108:111], v[180:183], v[28:31]
	v_mfma_f32_16x16x32_bf16 v[24:27], v[128:131], v[180:183], v[24:27]
	v_mfma_f32_16x16x32_bf16 v[12:15], v[108:111], v[210:213], v[12:15]
	v_mfma_f32_16x16x32_bf16 v[8:11], v[128:131], v[210:213], v[8:11]
	v_mfma_f32_16x16x32_bf16 v[52:55], v[144:147], v[160:163], v[52:55]
	v_mfma_f32_16x16x32_bf16 v[48:51], v[152:155], v[160:163], v[48:51]
	v_mfma_f32_16x16x32_bf16 v[36:39], v[144:147], v[168:171], v[36:39]
	v_mfma_f32_16x16x32_bf16 v[32:35], v[152:155], v[168:171], v[32:35]
	v_mfma_f32_16x16x32_bf16 v[20:23], v[144:147], v[176:179], v[20:23]
	v_mfma_f32_16x16x32_bf16 v[16:19], v[152:155], v[176:179], v[16:19]
	v_mfma_f32_16x16x32_bf16 v[4:7], v[144:147], v[206:209], v[4:7]
	v_mfma_f32_16x16x32_bf16 v[0:3], v[152:155], v[206:209], v[0:3]
	v_mfma_f32_16x16x32_bf16 v[52:55], v[148:151], v[164:167], v[52:55]
	v_mfma_f32_16x16x32_bf16 v[48:51], v[156:159], v[164:167], v[48:51]
	v_mfma_f32_16x16x32_bf16 v[36:39], v[148:151], v[172:175], v[36:39]
	v_mfma_f32_16x16x32_bf16 v[32:35], v[156:159], v[172:175], v[32:35]
	v_mfma_f32_16x16x32_bf16 v[20:23], v[148:151], v[180:183], v[20:23]
	v_mfma_f32_16x16x32_bf16 v[16:19], v[156:159], v[180:183], v[16:19]
	v_mfma_f32_16x16x32_bf16 v[4:7], v[148:151], v[210:213], v[4:7]
	v_mfma_f32_16x16x32_bf16 v[0:3], v[156:159], v[210:213], v[0:3]
	s_barrier
	s_setprio 0
	s_add_i32 s87, s87, 2
	s_add_u32 s46, s46, 0x100
	s_addc_u32 s47, s47, 0
	s_add_u32 s85, s85, 0x100
	s_addc_u32 s86, s86, 0
	s_cmp_gt_u32 s87, 13
	s_cbranch_scc0 .LBB0_504
	s_and_b64 vcc, exec, s[34:35]
	s_cbranch_vccz .LBB0_507
	s_barrier

.LBB0_552:
	ds_read_b128 v[128:131], v173
	ds_read_b128 v[132:135], v173 offset:1024
	ds_read_b128 v[136:139], v173 offset:2048
	ds_read_b128 v[140:143], v173 offset:3072
	ds_read_b128 v[160:163], v179
	ds_read_b128 v[174:177], v179 offset:1024
	ds_read_b128 v[194:197], v179 offset:2048
	ds_read_b128 v[198:201], v179 offset:3072
	s_add_u32 s57, s62, 0xfffc0080
	s_addc_u32 s64, s63, -1
	s_cmp_eq_u32 s55, 12
	s_cselect_b32 s67, s9, s64
	s_cselect_b32 s66, s11, s57
	s_cselect_b32 s65, s13, s23
	s_cselect_b32 s64, s16, s22
	s_add_i32 m0, s86, 0xc000
	ds_read_b128 v[202:205], v183
	ds_read_b128 v[206:209], v183 offset:1024
	ds_read_b128 v[210:213], v183 offset:2048
	ds_read_b128 v[214:217], v183 offset:3072
	ds_read_b128 v[218:221], v183 offset:4096
	ds_read_b128 v[222:225], v183 offset:5120
	ds_read_b128 v[226:229], v183 offset:6144
	ds_read_b128 v[230:233], v183 offset:7168
	global_load_lds_dwordx4 v152, s[62:63]
	s_add_i32 m0, s86, 0xe000
	s_nop 0
	global_load_lds_dwordx4 v154, s[62:63]
	s_waitcnt vmcnt(8)
	s_waitcnt lgkmcnt(0)
	s_setprio 1
	s_barrier
	v_mfma_f32_16x16x32_bf16 v[124:127], v[128:131], v[202:205], v[124:127]
	v_mfma_f32_16x16x32_bf16 v[120:123], v[136:139], v[202:205], v[120:123]
	v_mfma_f32_16x16x32_bf16 v[108:111], v[128:131], v[210:213], v[108:111]
	v_mfma_f32_16x16x32_bf16 v[104:107], v[136:139], v[210:213], v[104:107]
	v_mfma_f32_16x16x32_bf16 v[92:95], v[128:131], v[218:221], v[92:95]
	v_mfma_f32_16x16x32_bf16 v[88:91], v[136:139], v[218:221], v[88:91]
	v_mfma_f32_16x16x32_bf16 v[76:79], v[128:131], v[226:229], v[76:79]
	v_mfma_f32_16x16x32_bf16 v[72:75], v[136:139], v[226:229], v[72:75]
	v_mfma_f32_16x16x32_bf16 v[124:127], v[132:135], v[206:209], v[124:127]
	v_mfma_f32_16x16x32_bf16 v[120:123], v[140:143], v[206:209], v[120:123]
	v_mfma_f32_16x16x32_bf16 v[108:111], v[132:135], v[214:217], v[108:111]
	v_mfma_f32_16x16x32_bf16 v[104:107], v[140:143], v[214:217], v[104:107]
	v_mfma_f32_16x16x32_bf16 v[92:95], v[132:135], v[222:225], v[92:95]
	v_mfma_f32_16x16x32_bf16 v[88:91], v[140:143], v[222:225], v[88:91]
	v_mfma_f32_16x16x32_bf16 v[76:79], v[132:135], v[230:233], v[76:79]
	v_mfma_f32_16x16x32_bf16 v[72:75], v[140:143], v[230:233], v[72:75]
	v_mfma_f32_16x16x32_bf16 v[116:119], v[160:163], v[202:205], v[116:119]
	v_mfma_f32_16x16x32_bf16 v[112:115], v[194:197], v[202:205], v[112:115]
	v_mfma_f32_16x16x32_bf16 v[100:103], v[160:163], v[210:213], v[100:103]
	v_mfma_f32_16x16x32_bf16 v[96:99], v[194:197], v[210:213], v[96:99]
	v_mfma_f32_16x16x32_bf16 v[84:87], v[160:163], v[218:221], v[84:87]
	v_mfma_f32_16x16x32_bf16 v[80:83], v[194:197], v[218:221], v[80:83]
	v_mfma_f32_16x16x32_bf16 v[68:71], v[160:163], v[226:229], v[68:71]
	v_mfma_f32_16x16x32_bf16 v[64:67], v[194:197], v[226:229], v[64:67]
	v_mfma_f32_16x16x32_bf16 v[116:119], v[174:177], v[206:209], v[116:119]
	v_mfma_f32_16x16x32_bf16 v[112:115], v[198:201], v[206:209], v[112:115]
	v_mfma_f32_16x16x32_bf16 v[100:103], v[174:177], v[214:217], v[100:103]
	v_mfma_f32_16x16x32_bf16 v[96:99], v[198:201], v[214:217], v[96:99]
	v_mfma_f32_16x16x32_bf16 v[84:87], v[174:177], v[222:225], v[84:87]
	v_mfma_f32_16x16x32_bf16 v[80:83], v[198:201], v[222:225], v[80:83]
	v_mfma_f32_16x16x32_bf16 v[68:71], v[174:177], v[230:233], v[68:71]
	v_mfma_f32_16x16x32_bf16 v[64:67], v[198:201], v[230:233], v[64:67]
	s_barrier
	s_setprio 0
	s_add_i32 s57, s0, s85
	s_add_u32 s98, s64, 0x80
	s_addc_u32 s99, s65, 0
	s_mov_b32 m0, s57
	ds_read_b128 v[202:205], v183 offset:16384
	ds_read_b128 v[206:209], v183 offset:17408
	ds_read_b128 v[210:213], v183 offset:18432
	ds_read_b128 v[214:217], v183 offset:19456
	ds_read_b128 v[218:221], v183 offset:20480
	ds_read_b128 v[222:225], v183 offset:21504
	ds_read_b128 v[226:229], v183 offset:22528
	ds_read_b128 v[230:233], v183 offset:23552
	global_load_lds_dwordx4 v144, s[64:65]
	s_add_i32 m0, s57, 0x2000
	s_add_u32 s68, s64, 0x40000
	s_addc_u32 s69, s65, 0
	s_add_i32 s57, s1, s85
	global_load_lds_dwordx4 v146, s[64:65]
	s_mov_b32 m0, s57
	s_add_u32 s100, s66, 0x80
	s_addc_u32 s101, s67, 0
	global_load_lds_dwordx4 v144, s[68:69]
	s_add_i32 m0, s57, 0x2000
	s_nop 0
	global_load_lds_dwordx4 v146, s[68:69]
	s_mov_b32 m0, s86
	s_nop 0
	global_load_lds_dwordx4 v144, s[66:67]
	s_mov_b32 m0, s87
	s_nop 0
	global_load_lds_dwordx4 v146, s[66:67]
	s_waitcnt vmcnt(8)
	s_waitcnt lgkmcnt(0)
	s_setprio 1
	s_barrier
	v_mfma_f32_16x16x32_bf16 v[60:63], v[128:131], v[202:205], v[60:63]
	v_mfma_f32_16x16x32_bf16 v[56:59], v[136:139], v[202:205], v[56:59]
	v_mfma_f32_16x16x32_bf16 v[44:47], v[128:131], v[210:213], v[44:47]
	v_mfma_f32_16x16x32_bf16 v[40:43], v[136:139], v[210:213], v[40:43]
	v_mfma_f32_16x16x32_bf16 v[28:31], v[128:131], v[218:221], v[28:31]
	v_mfma_f32_16x16x32_bf16 v[24:27], v[136:139], v[218:221], v[24:27]
	v_mfma_f32_16x16x32_bf16 v[12:15], v[128:131], v[226:229], v[12:15]
	v_mfma_f32_16x16x32_bf16 v[8:11], v[136:139], v[226:229], v[8:11]
	v_mfma_f32_16x16x32_bf16 v[60:63], v[132:135], v[206:209], v[60:63]
	v_mfma_f32_16x16x32_bf16 v[56:59], v[140:143], v[206:209], v[56:59]
	v_mfma_f32_16x16x32_bf16 v[44:47], v[132:135], v[214:217], v[44:47]
	v_mfma_f32_16x16x32_bf16 v[40:43], v[140:143], v[214:217], v[40:43]
	v_mfma_f32_16x16x32_bf16 v[28:31], v[132:135], v[222:225], v[28:31]
	v_mfma_f32_16x16x32_bf16 v[24:27], v[140:143], v[222:225], v[24:27]
	v_mfma_f32_16x16x32_bf16 v[12:15], v[132:135], v[230:233], v[12:15]
	v_mfma_f32_16x16x32_bf16 v[8:11], v[140:143], v[230:233], v[8:11]
	v_mfma_f32_16x16x32_bf16 v[52:55], v[160:163], v[202:205], v[52:55]
	v_mfma_f32_16x16x32_bf16 v[48:51], v[194:197], v[202:205], v[48:51]
	v_mfma_f32_16x16x32_bf16 v[36:39], v[160:163], v[210:213], v[36:39]
	v_mfma_f32_16x16x32_bf16 v[32:35], v[194:197], v[210:213], v[32:35]
	v_mfma_f32_16x16x32_bf16 v[20:23], v[160:163], v[218:221], v[20:23]
	v_mfma_f32_16x16x32_bf16 v[16:19], v[194:197], v[218:221], v[16:19]
	v_mfma_f32_16x16x32_bf16 v[4:7], v[160:163], v[226:229], v[4:7]
	v_mfma_f32_16x16x32_bf16 v[0:3], v[194:197], v[226:229], v[0:3]
	v_mfma_f32_16x16x32_bf16 v[52:55], v[174:177], v[206:209], v[52:55]
	v_mfma_f32_16x16x32_bf16 v[48:51], v[198:201], v[206:209], v[48:51]
	v_mfma_f32_16x16x32_bf16 v[36:39], v[174:177], v[214:217], v[36:39]
	v_mfma_f32_16x16x32_bf16 v[32:35], v[198:201], v[214:217], v[32:35]
	v_mfma_f32_16x16x32_bf16 v[20:23], v[174:177], v[222:225], v[20:23]
	v_mfma_f32_16x16x32_bf16 v[16:19], v[198:201], v[222:225], v[16:19]
	v_mfma_f32_16x16x32_bf16 v[4:7], v[174:177], v[230:233], v[4:7]
	v_mfma_f32_16x16x32_bf16 v[0:3], v[198:201], v[230:233], v[0:3]
	s_barrier
	s_setprio 0
	s_add_i32 s57, 0, 0x18000
	s_add_i32 s68, 0, 0x1c000
	v_add_u32_e32 v140, s57, v169
	v_add_u32_e32 v148, s68, v169
	ds_read_b128 v[128:131], v140
	ds_read_b128 v[132:135], v140 offset:1024
	ds_read_b128 v[136:139], v140 offset:2048
	ds_read_b128 v[140:143], v140 offset:3072
	ds_read_b128 v[160:163], v148
	ds_read_b128 v[174:177], v148 offset:1024
	ds_read_b128 v[194:197], v148 offset:2048
	ds_read_b128 v[198:201], v148 offset:3072
	s_add_u32 s66, s66, 0x40000
	s_addc_u32 s67, s67, 0
	s_mov_b32 m0, s88
	ds_read_b128 v[202:205], v183 offset:32768
	ds_read_b128 v[206:209], v183 offset:33792
	ds_read_b128 v[210:213], v183 offset:34816
	ds_read_b128 v[214:217], v183 offset:35840
	ds_read_b128 v[218:221], v183 offset:36864
	ds_read_b128 v[222:225], v183 offset:37888
	ds_read_b128 v[226:229], v183 offset:38912
	ds_read_b128 v[230:233], v183 offset:39936
	global_load_lds_dwordx4 v144, s[66:67]
	s_mov_b32 m0, s89
	s_nop 0
	global_load_lds_dwordx4 v146, s[66:67]
	s_waitcnt vmcnt(8)
	s_waitcnt lgkmcnt(0)
	s_setprio 1
	s_barrier
	v_mfma_f32_16x16x32_bf16 v[124:127], v[128:131], v[202:205], v[124:127]
	v_mfma_f32_16x16x32_bf16 v[120:123], v[136:139], v[202:205], v[120:123]
	v_mfma_f32_16x16x32_bf16 v[108:111], v[128:131], v[210:213], v[108:111]
	v_mfma_f32_16x16x32_bf16 v[104:107], v[136:139], v[210:213], v[104:107]
	v_mfma_f32_16x16x32_bf16 v[92:95], v[128:131], v[218:221], v[92:95]
	v_mfma_f32_16x16x32_bf16 v[88:91], v[136:139], v[218:221], v[88:91]
	v_mfma_f32_16x16x32_bf16 v[76:79], v[128:131], v[226:229], v[76:79]
	v_mfma_f32_16x16x32_bf16 v[72:75], v[136:139], v[226:229], v[72:75]
	v_mfma_f32_16x16x32_bf16 v[124:127], v[132:135], v[206:209], v[124:127]
	v_mfma_f32_16x16x32_bf16 v[120:123], v[140:143], v[206:209], v[120:123]
	v_mfma_f32_16x16x32_bf16 v[108:111], v[132:135], v[214:217], v[108:111]
	v_mfma_f32_16x16x32_bf16 v[104:107], v[140:143], v[214:217], v[104:107]
	v_mfma_f32_16x16x32_bf16 v[92:95], v[132:135], v[222:225], v[92:95]
	v_mfma_f32_16x16x32_bf16 v[88:91], v[140:143], v[222:225], v[88:91]
	v_mfma_f32_16x16x32_bf16 v[76:79], v[132:135], v[230:233], v[76:79]
	v_mfma_f32_16x16x32_bf16 v[72:75], v[140:143], v[230:233], v[72:75]
	v_mfma_f32_16x16x32_bf16 v[116:119], v[160:163], v[202:205], v[116:119]
	v_mfma_f32_16x16x32_bf16 v[112:115], v[194:197], v[202:205], v[112:115]
	v_mfma_f32_16x16x32_bf16 v[100:103], v[160:163], v[210:213], v[100:103]
	v_mfma_f32_16x16x32_bf16 v[96:99], v[194:197], v[210:213], v[96:99]
	v_mfma_f32_16x16x32_bf16 v[84:87], v[160:163], v[218:221], v[84:87]
	v_mfma_f32_16x16x32_bf16 v[80:83], v[194:197], v[218:221], v[80:83]
	v_mfma_f32_16x16x32_bf16 v[68:71], v[160:163], v[226:229], v[68:71]
	v_mfma_f32_16x16x32_bf16 v[64:67], v[194:197], v[226:229], v[64:67]
	v_mfma_f32_16x16x32_bf16 v[116:119], v[174:177], v[206:209], v[116:119]
	v_mfma_f32_16x16x32_bf16 v[112:115], v[198:201], v[206:209], v[112:115]
	v_mfma_f32_16x16x32_bf16 v[100:103], v[174:177], v[214:217], v[100:103]
	v_mfma_f32_16x16x32_bf16 v[96:99], v[198:201], v[214:217], v[96:99]
	v_mfma_f32_16x16x32_bf16 v[84:87], v[174:177], v[222:225], v[84:87]
	v_mfma_f32_16x16x32_bf16 v[80:83], v[198:201], v[222:225], v[80:83]
	v_mfma_f32_16x16x32_bf16 v[68:71], v[174:177], v[230:233], v[68:71]
	v_mfma_f32_16x16x32_bf16 v[64:67], v[198:201], v[230:233], v[64:67]
	s_barrier
	s_setprio 0
	s_add_i32 s57, s57, s85
	s_mov_b32 m0, s57
	ds_read_b128 v[202:205], v183 offset:49152
	ds_read_b128 v[206:209], v183 offset:50176
	ds_read_b128 v[210:213], v183 offset:51200
	ds_read_b128 v[214:217], v183 offset:52224
	ds_read_b128 v[218:221], v183 offset:53248
	ds_read_b128 v[222:225], v183 offset:54272
	ds_read_b128 v[226:229], v183 offset:55296
	ds_read_b128 v[230:233], v183 offset:56320
	global_load_lds_dwordx4 v144, s[98:99]
	s_add_i32 m0, s57, 0x2000
	s_add_u32 s64, s64, 0x40080
	s_addc_u32 s65, s65, 0
	s_add_i32 s57, s68, s85
	global_load_lds_dwordx4 v146, s[98:99]
	s_mov_b32 m0, s57
	s_nop 0
	global_load_lds_dwordx4 v144, s[64:65]
	s_add_i32 m0, s57, 0x2000
	s_nop 0
	global_load_lds_dwordx4 v146, s[64:65]
	s_mov_b32 m0, s94
	s_nop 0
	global_load_lds_dwordx4 v144, s[100:101]
	s_mov_b32 m0, s95
	s_nop 0
	global_load_lds_dwordx4 v146, s[100:101]
	s_waitcnt vmcnt(8)
	s_waitcnt lgkmcnt(0)
	s_setprio 1
	s_barrier
	v_mfma_f32_16x16x32_bf16 v[60:63], v[128:131], v[202:205], v[60:63]
	v_mfma_f32_16x16x32_bf16 v[56:59], v[136:139], v[202:205], v[56:59]
	v_mfma_f32_16x16x32_bf16 v[44:47], v[128:131], v[210:213], v[44:47]
	v_mfma_f32_16x16x32_bf16 v[40:43], v[136:139], v[210:213], v[40:43]
	v_mfma_f32_16x16x32_bf16 v[28:31], v[128:131], v[218:221], v[28:31]
	v_mfma_f32_16x16x32_bf16 v[24:27], v[136:139], v[218:221], v[24:27]
	v_mfma_f32_16x16x32_bf16 v[12:15], v[128:131], v[226:229], v[12:15]
	v_mfma_f32_16x16x32_bf16 v[8:11], v[136:139], v[226:229], v[8:11]
	v_mfma_f32_16x16x32_bf16 v[60:63], v[132:135], v[206:209], v[60:63]
	v_mfma_f32_16x16x32_bf16 v[56:59], v[140:143], v[206:209], v[56:59]
	v_mfma_f32_16x16x32_bf16 v[44:47], v[132:135], v[214:217], v[44:47]
	v_mfma_f32_16x16x32_bf16 v[40:43], v[140:143], v[214:217], v[40:43]
	v_mfma_f32_16x16x32_bf16 v[28:31], v[132:135], v[222:225], v[28:31]
	v_mfma_f32_16x16x32_bf16 v[24:27], v[140:143], v[222:225], v[24:27]
	v_mfma_f32_16x16x32_bf16 v[12:15], v[132:135], v[230:233], v[12:15]
	v_mfma_f32_16x16x32_bf16 v[8:11], v[140:143], v[230:233], v[8:11]
	v_mfma_f32_16x16x32_bf16 v[52:55], v[160:163], v[202:205], v[52:55]
	v_mfma_f32_16x16x32_bf16 v[48:51], v[194:197], v[202:205], v[48:51]
	v_mfma_f32_16x16x32_bf16 v[36:39], v[160:163], v[210:213], v[36:39]
	v_mfma_f32_16x16x32_bf16 v[32:35], v[194:197], v[210:213], v[32:35]
	v_mfma_f32_16x16x32_bf16 v[20:23], v[160:163], v[218:221], v[20:23]
	v_mfma_f32_16x16x32_bf16 v[16:19], v[194:197], v[218:221], v[16:19]
	v_mfma_f32_16x16x32_bf16 v[4:7], v[160:163], v[226:229], v[4:7]
	v_mfma_f32_16x16x32_bf16 v[0:3], v[194:197], v[226:229], v[0:3]
	v_mfma_f32_16x16x32_bf16 v[52:55], v[174:177], v[206:209], v[52:55]
	v_mfma_f32_16x16x32_bf16 v[48:51], v[198:201], v[206:209], v[48:51]
	v_mfma_f32_16x16x32_bf16 v[36:39], v[174:177], v[214:217], v[36:39]
	v_mfma_f32_16x16x32_bf16 v[32:35], v[198:201], v[214:217], v[32:35]
	v_mfma_f32_16x16x32_bf16 v[20:23], v[174:177], v[222:225], v[20:23]
	v_mfma_f32_16x16x32_bf16 v[16:19], v[198:201], v[222:225], v[16:19]
	v_mfma_f32_16x16x32_bf16 v[4:7], v[174:177], v[230:233], v[4:7]
	v_mfma_f32_16x16x32_bf16 v[0:3], v[198:201], v[230:233], v[0:3]
	s_barrier
	s_setprio 0
	s_add_i32 s55, s55, 2
	s_add_u32 s62, s62, 0x100
	s_addc_u32 s63, s63, 0
	s_add_u32 s22, s22, 0x100
	s_addc_u32 s23, s23, 0
	s_cmp_gt_u32 s55, 13
	s_cbranch_scc0 .LBB0_552
	s_and_b64 vcc, exec, s[44:45]
	s_cbranch_vccz .LBB0_555
	s_barrier

.LBB0_771:
	ds_read_b128 v[84:87], v208
	ds_read_b128 v[100:103], v208 offset:1024
	ds_read_b128 v[120:123], v208 offset:2048
	ds_read_b128 v[140:143], v208 offset:3072
	ds_read_b128 v[144:147], v209
	ds_read_b128 v[148:151], v209 offset:1024
	ds_read_b128 v[152:155], v209 offset:2048
	ds_read_b128 v[170:173], v209 offset:3072
	s_add_u32 s6, s8, 0x100
	s_addc_u32 s7, s9, 0
	s_cmp_eq_u32 s83, 2
	s_cselect_b32 s41, s35, s7
	s_cselect_b32 s40, s34, s6
	s_cselect_b32 s39, s37, s82
	s_cselect_b32 s38, s36, s81
	s_add_i32 m0, s42, 0xc000
	ds_read_b128 v[174:177], v210
	ds_read_b128 v[178:181], v210 offset:1024
	ds_read_b128 v[182:185], v210 offset:2048
	ds_read_b128 v[186:189], v210 offset:3072
	ds_read_b128 v[190:193], v210 offset:4096
	ds_read_b128 v[194:197], v210 offset:5120
	ds_read_b128 v[198:201], v210 offset:6144
	ds_read_b128 v[202:205], v210 offset:7168
	global_load_lds_dwordx4 v162, s[8:9]
	s_add_i32 m0, s42, 0xe000
	s_nop 0
	global_load_lds_dwordx4 v164, s[8:9]
	s_waitcnt vmcnt(8)
	s_waitcnt lgkmcnt(0)
	s_setprio 1
	s_barrier
	v_mfma_f32_16x16x32_bf16 v[136:139], v[84:87], v[174:177], v[136:139]
	v_mfma_f32_16x16x32_bf16 v[132:135], v[120:123], v[174:177], v[132:135]
	v_mfma_f32_16x16x32_bf16 v[116:119], v[84:87], v[182:185], v[116:119]
	v_mfma_f32_16x16x32_bf16 v[112:115], v[120:123], v[182:185], v[112:115]
	v_mfma_f32_16x16x32_bf16 v[96:99], v[84:87], v[190:193], v[96:99]
	v_mfma_f32_16x16x32_bf16 v[92:95], v[120:123], v[190:193], v[92:95]
	v_mfma_f32_16x16x32_bf16 v[76:79], v[84:87], v[198:201], v[76:79]
	v_mfma_f32_16x16x32_bf16 v[72:75], v[120:123], v[198:201], v[72:75]
	v_mfma_f32_16x16x32_bf16 v[136:139], v[100:103], v[178:181], v[136:139]
	v_mfma_f32_16x16x32_bf16 v[132:135], v[140:143], v[178:181], v[132:135]
	v_mfma_f32_16x16x32_bf16 v[116:119], v[100:103], v[186:189], v[116:119]
	v_mfma_f32_16x16x32_bf16 v[112:115], v[140:143], v[186:189], v[112:115]
	v_mfma_f32_16x16x32_bf16 v[96:99], v[100:103], v[194:197], v[96:99]
	v_mfma_f32_16x16x32_bf16 v[92:95], v[140:143], v[194:197], v[92:95]
	v_mfma_f32_16x16x32_bf16 v[76:79], v[100:103], v[202:205], v[76:79]
	v_mfma_f32_16x16x32_bf16 v[72:75], v[140:143], v[202:205], v[72:75]
	v_mfma_f32_16x16x32_bf16 v[128:131], v[144:147], v[174:177], v[128:131]
	v_mfma_f32_16x16x32_bf16 v[124:127], v[152:155], v[174:177], v[124:127]
	v_mfma_f32_16x16x32_bf16 v[108:111], v[144:147], v[182:185], v[108:111]
	v_mfma_f32_16x16x32_bf16 v[104:107], v[152:155], v[182:185], v[104:107]
	v_mfma_f32_16x16x32_bf16 v[88:91], v[144:147], v[190:193], v[88:91]
	v_mfma_f32_16x16x32_bf16 v[80:83], v[152:155], v[190:193], v[80:83]
	v_mfma_f32_16x16x32_bf16 v[68:71], v[144:147], v[198:201], v[68:71]
	v_mfma_f32_16x16x32_bf16 v[64:67], v[152:155], v[198:201], v[64:67]
	v_mfma_f32_16x16x32_bf16 v[128:131], v[148:151], v[178:181], v[128:131]
	v_mfma_f32_16x16x32_bf16 v[124:127], v[170:173], v[178:181], v[124:127]
	v_mfma_f32_16x16x32_bf16 v[108:111], v[148:151], v[186:189], v[108:111]
	v_mfma_f32_16x16x32_bf16 v[104:107], v[170:173], v[186:189], v[104:107]
	v_mfma_f32_16x16x32_bf16 v[88:91], v[148:151], v[194:197], v[88:91]
	v_mfma_f32_16x16x32_bf16 v[80:83], v[170:173], v[194:197], v[80:83]
	v_mfma_f32_16x16x32_bf16 v[68:71], v[148:151], v[202:205], v[68:71]
	v_mfma_f32_16x16x32_bf16 v[64:67], v[170:173], v[202:205], v[64:67]
	s_barrier
	s_setprio 0
	s_add_i32 s8, s61, s3
	s_add_u32 s98, s38, 0x80
	s_addc_u32 s99, s39, 0
	s_mov_b32 m0, s8
	ds_read_b128 v[174:177], v210 offset:16384
	ds_read_b128 v[178:181], v210 offset:17408
	ds_read_b128 v[182:185], v210 offset:18432
	ds_read_b128 v[186:189], v210 offset:19456
	ds_read_b128 v[190:193], v210 offset:20480
	ds_read_b128 v[194:197], v210 offset:21504
	ds_read_b128 v[198:201], v210 offset:22528
	ds_read_b128 v[202:205], v210 offset:23552
	global_load_lds_dwordx4 v156, s[38:39]
	s_add_i32 m0, s8, 0x2000
	s_add_u32 s8, s38, 0x18000
	s_addc_u32 s9, s39, 0
	s_add_i32 s84, s62, s3
	global_load_lds_dwordx4 v158, s[38:39]
	s_mov_b32 m0, s84
	s_add_u32 s100, s40, 0x80
	s_addc_u32 s101, s41, 0
	global_load_lds_dwordx4 v156, s[8:9]
	s_add_i32 m0, s84, 0x2000
	s_nop 0
	global_load_lds_dwordx4 v158, s[8:9]
	s_mov_b32 m0, s42
	s_nop 0
	global_load_lds_dwordx4 v156, s[40:41]
	s_mov_b32 m0, s43
	s_nop 0
	global_load_lds_dwordx4 v158, s[40:41]
	s_waitcnt vmcnt(8)
	s_waitcnt lgkmcnt(0)
	s_setprio 1
	s_barrier
	v_mfma_f32_16x16x32_bf16 v[60:63], v[84:87], v[174:177], v[60:63]
	v_mfma_f32_16x16x32_bf16 v[56:59], v[120:123], v[174:177], v[56:59]
	v_mfma_f32_16x16x32_bf16 v[44:47], v[84:87], v[182:185], v[44:47]
	v_mfma_f32_16x16x32_bf16 v[40:43], v[120:123], v[182:185], v[40:43]
	v_mfma_f32_16x16x32_bf16 v[28:31], v[84:87], v[190:193], v[28:31]
	v_mfma_f32_16x16x32_bf16 v[24:27], v[120:123], v[190:193], v[24:27]
	v_mfma_f32_16x16x32_bf16 v[12:15], v[84:87], v[198:201], v[12:15]
	v_mfma_f32_16x16x32_bf16 v[8:11], v[120:123], v[198:201], v[8:11]
	v_mfma_f32_16x16x32_bf16 v[60:63], v[100:103], v[178:181], v[60:63]
	v_mfma_f32_16x16x32_bf16 v[56:59], v[140:143], v[178:181], v[56:59]
	v_mfma_f32_16x16x32_bf16 v[44:47], v[100:103], v[186:189], v[44:47]
	v_mfma_f32_16x16x32_bf16 v[40:43], v[140:143], v[186:189], v[40:43]
	v_mfma_f32_16x16x32_bf16 v[28:31], v[100:103], v[194:197], v[28:31]
	v_mfma_f32_16x16x32_bf16 v[24:27], v[140:143], v[194:197], v[24:27]
	v_mfma_f32_16x16x32_bf16 v[12:15], v[100:103], v[202:205], v[12:15]
	v_mfma_f32_16x16x32_bf16 v[8:11], v[140:143], v[202:205], v[8:11]
	v_mfma_f32_16x16x32_bf16 v[52:55], v[144:147], v[174:177], v[52:55]
	v_mfma_f32_16x16x32_bf16 v[48:51], v[152:155], v[174:177], v[48:51]
	v_mfma_f32_16x16x32_bf16 v[36:39], v[144:147], v[182:185], v[36:39]
	v_mfma_f32_16x16x32_bf16 v[32:35], v[152:155], v[182:185], v[32:35]
	v_mfma_f32_16x16x32_bf16 v[20:23], v[144:147], v[190:193], v[20:23]
	v_mfma_f32_16x16x32_bf16 v[16:19], v[152:155], v[190:193], v[16:19]
	v_mfma_f32_16x16x32_bf16 v[4:7], v[144:147], v[198:201], v[4:7]
	v_mfma_f32_16x16x32_bf16 v[0:3], v[152:155], v[198:201], v[0:3]
	v_mfma_f32_16x16x32_bf16 v[52:55], v[148:151], v[178:181], v[52:55]
	v_mfma_f32_16x16x32_bf16 v[48:51], v[170:173], v[178:181], v[48:51]
	v_mfma_f32_16x16x32_bf16 v[36:39], v[148:151], v[186:189], v[36:39]
	v_mfma_f32_16x16x32_bf16 v[32:35], v[170:173], v[186:189], v[32:35]
	v_mfma_f32_16x16x32_bf16 v[20:23], v[148:151], v[194:197], v[20:23]
	v_mfma_f32_16x16x32_bf16 v[16:19], v[170:173], v[194:197], v[16:19]
	v_mfma_f32_16x16x32_bf16 v[4:7], v[148:151], v[202:205], v[4:7]
	v_mfma_f32_16x16x32_bf16 v[0:3], v[170:173], v[202:205], v[0:3]
	s_barrier
	s_setprio 0
	s_add_i32 s84, 0, 0x18000
	s_add_i32 s85, 0, 0x1c000
	v_add_u32_e32 v140, s84, v207
	v_add_u32_e32 v160, s85, v207
	ds_read_b128 v[84:87], v140
	ds_read_b128 v[100:103], v140 offset:1024
	ds_read_b128 v[120:123], v140 offset:2048
	ds_read_b128 v[140:143], v140 offset:3072
	ds_read_b128 v[144:147], v160
	ds_read_b128 v[148:151], v160 offset:1024
	ds_read_b128 v[152:155], v160 offset:2048
	ds_read_b128 v[170:173], v160 offset:3072
	s_add_u32 s8, s40, 0x18000
	s_addc_u32 s9, s41, 0
	s_mov_b32 m0, s44
	ds_read_b128 v[174:177], v210 offset:32768
	ds_read_b128 v[178:181], v210 offset:33792
	ds_read_b128 v[182:185], v210 offset:34816
	ds_read_b128 v[186:189], v210 offset:35840
	ds_read_b128 v[190:193], v210 offset:36864
	ds_read_b128 v[194:197], v210 offset:37888
	ds_read_b128 v[198:201], v210 offset:38912
	ds_read_b128 v[202:205], v210 offset:39936
	global_load_lds_dwordx4 v156, s[8:9]
	s_mov_b32 m0, s45
	s_nop 0
	global_load_lds_dwordx4 v158, s[8:9]
	s_waitcnt vmcnt(8)
	s_waitcnt lgkmcnt(0)
	s_setprio 1
	s_barrier
	v_mfma_f32_16x16x32_bf16 v[136:139], v[84:87], v[174:177], v[136:139]
	v_mfma_f32_16x16x32_bf16 v[132:135], v[120:123], v[174:177], v[132:135]
	v_mfma_f32_16x16x32_bf16 v[116:119], v[84:87], v[182:185], v[116:119]
	v_mfma_f32_16x16x32_bf16 v[112:115], v[120:123], v[182:185], v[112:115]
	v_mfma_f32_16x16x32_bf16 v[96:99], v[84:87], v[190:193], v[96:99]
	v_mfma_f32_16x16x32_bf16 v[92:95], v[120:123], v[190:193], v[92:95]
	v_mfma_f32_16x16x32_bf16 v[76:79], v[84:87], v[198:201], v[76:79]
	v_mfma_f32_16x16x32_bf16 v[72:75], v[120:123], v[198:201], v[72:75]
	v_mfma_f32_16x16x32_bf16 v[136:139], v[100:103], v[178:181], v[136:139]
	v_mfma_f32_16x16x32_bf16 v[132:135], v[140:143], v[178:181], v[132:135]
	v_mfma_f32_16x16x32_bf16 v[116:119], v[100:103], v[186:189], v[116:119]
	v_mfma_f32_16x16x32_bf16 v[112:115], v[140:143], v[186:189], v[112:115]
	v_mfma_f32_16x16x32_bf16 v[96:99], v[100:103], v[194:197], v[96:99]
	v_mfma_f32_16x16x32_bf16 v[92:95], v[140:143], v[194:197], v[92:95]
	v_mfma_f32_16x16x32_bf16 v[76:79], v[100:103], v[202:205], v[76:79]
	v_mfma_f32_16x16x32_bf16 v[72:75], v[140:143], v[202:205], v[72:75]
	v_mfma_f32_16x16x32_bf16 v[128:131], v[144:147], v[174:177], v[128:131]
	v_mfma_f32_16x16x32_bf16 v[124:127], v[152:155], v[174:177], v[124:127]
	v_mfma_f32_16x16x32_bf16 v[108:111], v[144:147], v[182:185], v[108:111]
	v_mfma_f32_16x16x32_bf16 v[104:107], v[152:155], v[182:185], v[104:107]
	v_mfma_f32_16x16x32_bf16 v[88:91], v[144:147], v[190:193], v[88:91]
	v_mfma_f32_16x16x32_bf16 v[80:83], v[152:155], v[190:193], v[80:83]
	v_mfma_f32_16x16x32_bf16 v[68:71], v[144:147], v[198:201], v[68:71]
	v_mfma_f32_16x16x32_bf16 v[64:67], v[152:155], v[198:201], v[64:67]
	v_mfma_f32_16x16x32_bf16 v[128:131], v[148:151], v[178:181], v[128:131]
	v_mfma_f32_16x16x32_bf16 v[124:127], v[170:173], v[178:181], v[124:127]
	v_mfma_f32_16x16x32_bf16 v[108:111], v[148:151], v[186:189], v[108:111]
	v_mfma_f32_16x16x32_bf16 v[104:107], v[170:173], v[186:189], v[104:107]
	v_mfma_f32_16x16x32_bf16 v[88:91], v[148:151], v[194:197], v[88:91]
	v_mfma_f32_16x16x32_bf16 v[80:83], v[170:173], v[194:197], v[80:83]
	v_mfma_f32_16x16x32_bf16 v[68:71], v[148:151], v[202:205], v[68:71]
	v_mfma_f32_16x16x32_bf16 v[64:67], v[170:173], v[202:205], v[64:67]
	s_barrier
	s_setprio 0
	s_add_i32 s8, s84, s3
	s_mov_b32 m0, s8
	ds_read_b128 v[174:177], v210 offset:49152
	ds_read_b128 v[178:181], v210 offset:50176
	ds_read_b128 v[182:185], v210 offset:51200
	ds_read_b128 v[186:189], v210 offset:52224
	ds_read_b128 v[190:193], v210 offset:53248
	ds_read_b128 v[194:197], v210 offset:54272
	ds_read_b128 v[198:201], v210 offset:55296
	ds_read_b128 v[202:205], v210 offset:56320
	global_load_lds_dwordx4 v156, s[98:99]
	s_add_i32 m0, s8, 0x2000
	s_add_u32 s8, s38, 0x18080
	s_addc_u32 s9, s39, 0
	s_add_i32 s38, s85, s3
	global_load_lds_dwordx4 v158, s[98:99]
	s_mov_b32 m0, s38
	s_nop 0
	global_load_lds_dwordx4 v156, s[8:9]
	s_add_i32 m0, s38, 0x2000
	s_nop 0
	global_load_lds_dwordx4 v158, s[8:9]
	s_mov_b32 m0, s51
	s_nop 0
	global_load_lds_dwordx4 v156, s[100:101]
	s_mov_b32 m0, s52
	s_nop 0
	global_load_lds_dwordx4 v158, s[100:101]
	s_waitcnt vmcnt(8)
	s_waitcnt lgkmcnt(0)
	s_setprio 1
	s_barrier
	v_mfma_f32_16x16x32_bf16 v[60:63], v[84:87], v[174:177], v[60:63]
	v_mfma_f32_16x16x32_bf16 v[56:59], v[120:123], v[174:177], v[56:59]
	v_mfma_f32_16x16x32_bf16 v[44:47], v[84:87], v[182:185], v[44:47]
	v_mfma_f32_16x16x32_bf16 v[40:43], v[120:123], v[182:185], v[40:43]
	v_mfma_f32_16x16x32_bf16 v[28:31], v[84:87], v[190:193], v[28:31]
	v_mfma_f32_16x16x32_bf16 v[24:27], v[120:123], v[190:193], v[24:27]
	v_mfma_f32_16x16x32_bf16 v[12:15], v[84:87], v[198:201], v[12:15]
	v_mfma_f32_16x16x32_bf16 v[8:11], v[120:123], v[198:201], v[8:11]
	v_mfma_f32_16x16x32_bf16 v[60:63], v[100:103], v[178:181], v[60:63]
	v_mfma_f32_16x16x32_bf16 v[56:59], v[140:143], v[178:181], v[56:59]
	v_mfma_f32_16x16x32_bf16 v[44:47], v[100:103], v[186:189], v[44:47]
	v_mfma_f32_16x16x32_bf16 v[40:43], v[140:143], v[186:189], v[40:43]
	v_mfma_f32_16x16x32_bf16 v[28:31], v[100:103], v[194:197], v[28:31]
	v_mfma_f32_16x16x32_bf16 v[24:27], v[140:143], v[194:197], v[24:27]
	v_mfma_f32_16x16x32_bf16 v[12:15], v[100:103], v[202:205], v[12:15]
	v_mfma_f32_16x16x32_bf16 v[8:11], v[140:143], v[202:205], v[8:11]
	v_mfma_f32_16x16x32_bf16 v[52:55], v[144:147], v[174:177], v[52:55]
	v_mfma_f32_16x16x32_bf16 v[48:51], v[152:155], v[174:177], v[48:51]
	v_mfma_f32_16x16x32_bf16 v[36:39], v[144:147], v[182:185], v[36:39]
	v_mfma_f32_16x16x32_bf16 v[32:35], v[152:155], v[182:185], v[32:35]
	v_mfma_f32_16x16x32_bf16 v[20:23], v[144:147], v[190:193], v[20:23]
	v_mfma_f32_16x16x32_bf16 v[16:19], v[152:155], v[190:193], v[16:19]
	v_mfma_f32_16x16x32_bf16 v[4:7], v[144:147], v[198:201], v[4:7]
	v_mfma_f32_16x16x32_bf16 v[0:3], v[152:155], v[198:201], v[0:3]
	v_mfma_f32_16x16x32_bf16 v[52:55], v[148:151], v[178:181], v[52:55]
	v_mfma_f32_16x16x32_bf16 v[48:51], v[170:173], v[178:181], v[48:51]
	v_mfma_f32_16x16x32_bf16 v[36:39], v[148:151], v[186:189], v[36:39]
	v_mfma_f32_16x16x32_bf16 v[32:35], v[170:173], v[186:189], v[32:35]
	v_mfma_f32_16x16x32_bf16 v[20:23], v[148:151], v[194:197], v[20:23]
	v_mfma_f32_16x16x32_bf16 v[16:19], v[170:173], v[194:197], v[16:19]
	v_mfma_f32_16x16x32_bf16 v[4:7], v[148:151], v[202:205], v[4:7]
	v_mfma_f32_16x16x32_bf16 v[0:3], v[170:173], v[202:205], v[0:3]
	s_barrier
	s_setprio 0
	s_add_i32 s83, s83, 2
	s_add_u32 s81, s81, 0x100
	s_addc_u32 s82, s82, 0
	s_cmp_gt_u32 s83, 3
	s_mov_b64 s[8:9], s[6:7]
	s_cbranch_scc0 .LBB0_771
	s_and_b64 vcc, exec, s[30:31]
	s_cbranch_vccz .LBB0_774
	s_barrier

.LBB0_938:
	ds_read_b128 v[128:131], v175
	ds_read_b128 v[132:135], v175 offset:1024
	ds_read_b128 v[136:139], v175 offset:2048
	ds_read_b128 v[140:143], v175 offset:3072
	ds_read_b128 v[144:147], v176
	ds_read_b128 v[148:151], v176 offset:1024
	ds_read_b128 v[168:171], v176 offset:2048
	ds_read_b128 v[182:185], v176 offset:3072
	s_add_u32 s36, s6, 0xfffe0080
	s_addc_u32 s37, s7, -1
	s_cmp_eq_u32 s42, 4
	s_cselect_b32 s39, s9, s37
	s_cselect_b32 s38, s27, s36
	s_cselect_b32 s37, s23, s41
	s_cselect_b32 s36, s35, s40
	s_add_i32 m0, s48, 0xc000
	ds_read_b128 v[186:189], v177
	ds_read_b128 v[190:193], v177 offset:1024
	ds_read_b128 v[194:197], v177 offset:2048
	ds_read_b128 v[198:201], v177 offset:3072
	ds_read_b128 v[202:205], v177 offset:4096
	ds_read_b128 v[206:209], v177 offset:5120
	ds_read_b128 v[210:213], v177 offset:6144
	ds_read_b128 v[214:217], v177 offset:7168
	global_load_lds_dwordx4 v158, s[6:7]
	s_add_i32 m0, s48, 0xe000
	s_nop 0
	global_load_lds_dwordx4 v160, s[6:7]
	s_waitcnt vmcnt(8)
	s_waitcnt lgkmcnt(0)
	s_setprio 1
	s_barrier
	v_mfma_f32_16x16x32_bf16 v[124:127], v[128:131], v[186:189], v[124:127]
	v_mfma_f32_16x16x32_bf16 v[120:123], v[136:139], v[186:189], v[120:123]
	v_mfma_f32_16x16x32_bf16 v[112:115], v[128:131], v[194:197], v[112:115]
	v_mfma_f32_16x16x32_bf16 v[116:119], v[136:139], v[194:197], v[116:119]
	v_mfma_f32_16x16x32_bf16 v[96:99], v[128:131], v[202:205], v[96:99]
	v_mfma_f32_16x16x32_bf16 v[104:107], v[136:139], v[202:205], v[104:107]
	v_mfma_f32_16x16x32_bf16 v[76:79], v[128:131], v[210:213], v[76:79]
	v_mfma_f32_16x16x32_bf16 v[72:75], v[136:139], v[210:213], v[72:75]
	v_mfma_f32_16x16x32_bf16 v[124:127], v[132:135], v[190:193], v[124:127]
	v_mfma_f32_16x16x32_bf16 v[120:123], v[140:143], v[190:193], v[120:123]
	v_mfma_f32_16x16x32_bf16 v[112:115], v[132:135], v[198:201], v[112:115]
	v_mfma_f32_16x16x32_bf16 v[116:119], v[140:143], v[198:201], v[116:119]
	v_mfma_f32_16x16x32_bf16 v[96:99], v[132:135], v[206:209], v[96:99]
	v_mfma_f32_16x16x32_bf16 v[104:107], v[140:143], v[206:209], v[104:107]
	v_mfma_f32_16x16x32_bf16 v[76:79], v[132:135], v[214:217], v[76:79]
	v_mfma_f32_16x16x32_bf16 v[72:75], v[140:143], v[214:217], v[72:75]
	v_mfma_f32_16x16x32_bf16 v[108:111], v[144:147], v[186:189], v[108:111]
	v_mfma_f32_16x16x32_bf16 v[100:103], v[168:171], v[186:189], v[100:103]
	v_mfma_f32_16x16x32_bf16 v[88:91], v[144:147], v[194:197], v[88:91]
	v_mfma_f32_16x16x32_bf16 v[92:95], v[168:171], v[194:197], v[92:95]
	v_mfma_f32_16x16x32_bf16 v[84:87], v[144:147], v[202:205], v[84:87]
	v_mfma_f32_16x16x32_bf16 v[80:83], v[168:171], v[202:205], v[80:83]
	v_mfma_f32_16x16x32_bf16 v[68:71], v[144:147], v[210:213], v[68:71]
	v_mfma_f32_16x16x32_bf16 v[64:67], v[168:171], v[210:213], v[64:67]
	v_mfma_f32_16x16x32_bf16 v[108:111], v[148:151], v[190:193], v[108:111]
	v_mfma_f32_16x16x32_bf16 v[100:103], v[182:185], v[190:193], v[100:103]
	v_mfma_f32_16x16x32_bf16 v[88:91], v[148:151], v[198:201], v[88:91]
	v_mfma_f32_16x16x32_bf16 v[92:95], v[182:185], v[198:201], v[92:95]
	v_mfma_f32_16x16x32_bf16 v[84:87], v[148:151], v[206:209], v[84:87]
	v_mfma_f32_16x16x32_bf16 v[80:83], v[182:185], v[206:209], v[80:83]
	v_mfma_f32_16x16x32_bf16 v[68:71], v[148:151], v[214:217], v[68:71]
	v_mfma_f32_16x16x32_bf16 v[64:67], v[182:185], v[214:217], v[64:67]
	s_barrier
	s_setprio 0
	s_add_i32 s43, s72, s47
	s_add_u32 s98, s36, 0x80
	s_addc_u32 s99, s37, 0
	s_mov_b32 m0, s43
	ds_read_b128 v[186:189], v177 offset:16384
	ds_read_b128 v[190:193], v177 offset:17408
	ds_read_b128 v[194:197], v177 offset:18432
	ds_read_b128 v[198:201], v177 offset:19456
	ds_read_b128 v[202:205], v177 offset:20480
	ds_read_b128 v[206:209], v177 offset:21504
	ds_read_b128 v[210:213], v177 offset:22528
	ds_read_b128 v[214:217], v177 offset:23552
	global_load_lds_dwordx4 v152, s[36:37]
	s_add_i32 m0, s43, 0x2000
	s_add_u32 s88, s36, 0x20000
	s_addc_u32 s89, s37, 0
	s_add_i32 s43, s73, s47
	global_load_lds_dwordx4 v154, s[36:37]
	s_mov_b32 m0, s43
	s_add_u32 s100, s38, 0x80
	s_addc_u32 s101, s39, 0
	global_load_lds_dwordx4 v152, s[88:89]
	s_add_i32 m0, s43, 0x2000
	s_nop 0
	global_load_lds_dwordx4 v154, s[88:89]
	s_mov_b32 m0, s48
	s_nop 0
	global_load_lds_dwordx4 v152, s[38:39]
	s_mov_b32 m0, s49
	s_nop 0
	global_load_lds_dwordx4 v154, s[38:39]
	s_waitcnt vmcnt(8)
	s_waitcnt lgkmcnt(0)
	s_setprio 1
	s_barrier
	v_mfma_f32_16x16x32_bf16 v[60:63], v[128:131], v[186:189], v[60:63]
	v_mfma_f32_16x16x32_bf16 v[56:59], v[136:139], v[186:189], v[56:59]
	v_mfma_f32_16x16x32_bf16 v[44:47], v[128:131], v[194:197], v[44:47]
	v_mfma_f32_16x16x32_bf16 v[40:43], v[136:139], v[194:197], v[40:43]
	v_mfma_f32_16x16x32_bf16 v[28:31], v[128:131], v[202:205], v[28:31]
	v_mfma_f32_16x16x32_bf16 v[24:27], v[136:139], v[202:205], v[24:27]
	v_mfma_f32_16x16x32_bf16 v[12:15], v[128:131], v[210:213], v[12:15]
	v_mfma_f32_16x16x32_bf16 v[8:11], v[136:139], v[210:213], v[8:11]
	v_mfma_f32_16x16x32_bf16 v[60:63], v[132:135], v[190:193], v[60:63]
	v_mfma_f32_16x16x32_bf16 v[56:59], v[140:143], v[190:193], v[56:59]
	v_mfma_f32_16x16x32_bf16 v[44:47], v[132:135], v[198:201], v[44:47]
	v_mfma_f32_16x16x32_bf16 v[40:43], v[140:143], v[198:201], v[40:43]
	v_mfma_f32_16x16x32_bf16 v[28:31], v[132:135], v[206:209], v[28:31]
	v_mfma_f32_16x16x32_bf16 v[24:27], v[140:143], v[206:209], v[24:27]
	v_mfma_f32_16x16x32_bf16 v[12:15], v[132:135], v[214:217], v[12:15]
	v_mfma_f32_16x16x32_bf16 v[8:11], v[140:143], v[214:217], v[8:11]
	v_mfma_f32_16x16x32_bf16 v[52:55], v[144:147], v[186:189], v[52:55]
	v_mfma_f32_16x16x32_bf16 v[48:51], v[168:171], v[186:189], v[48:51]
	v_mfma_f32_16x16x32_bf16 v[36:39], v[144:147], v[194:197], v[36:39]
	v_mfma_f32_16x16x32_bf16 v[32:35], v[168:171], v[194:197], v[32:35]
	v_mfma_f32_16x16x32_bf16 v[20:23], v[144:147], v[202:205], v[20:23]
	v_mfma_f32_16x16x32_bf16 v[16:19], v[168:171], v[202:205], v[16:19]
	v_mfma_f32_16x16x32_bf16 v[4:7], v[144:147], v[210:213], v[4:7]
	v_mfma_f32_16x16x32_bf16 v[0:3], v[168:171], v[210:213], v[0:3]
	v_mfma_f32_16x16x32_bf16 v[52:55], v[148:151], v[190:193], v[52:55]
	v_mfma_f32_16x16x32_bf16 v[48:51], v[182:185], v[190:193], v[48:51]
	v_mfma_f32_16x16x32_bf16 v[36:39], v[148:151], v[198:201], v[36:39]
	v_mfma_f32_16x16x32_bf16 v[32:35], v[182:185], v[198:201], v[32:35]
	v_mfma_f32_16x16x32_bf16 v[20:23], v[148:151], v[206:209], v[20:23]
	v_mfma_f32_16x16x32_bf16 v[16:19], v[182:185], v[206:209], v[16:19]
	v_mfma_f32_16x16x32_bf16 v[4:7], v[148:151], v[214:217], v[4:7]
	v_mfma_f32_16x16x32_bf16 v[0:3], v[182:185], v[214:217], v[0:3]
	s_barrier
	s_setprio 0
	s_add_i32 s43, 0, 0x18000
	s_add_i32 s88, 0, 0x1c000
	v_add_u32_e32 v140, s43, v173
	v_add_u32_e32 v156, s88, v173
	ds_read_b128 v[128:131], v140
	ds_read_b128 v[132:135], v140 offset:1024
	ds_read_b128 v[136:139], v140 offset:2048
	ds_read_b128 v[140:143], v140 offset:3072
	ds_read_b128 v[144:147], v156
	ds_read_b128 v[148:151], v156 offset:1024
	ds_read_b128 v[168:171], v156 offset:2048
	ds_read_b128 v[182:185], v156 offset:3072
	s_add_u32 s38, s38, 0x20000
	s_addc_u32 s39, s39, 0
	s_mov_b32 m0, s50
	ds_read_b128 v[186:189], v177 offset:32768
	ds_read_b128 v[190:193], v177 offset:33792
	ds_read_b128 v[194:197], v177 offset:34816
	ds_read_b128 v[198:201], v177 offset:35840
	ds_read_b128 v[202:205], v177 offset:36864
	ds_read_b128 v[206:209], v177 offset:37888
	ds_read_b128 v[210:213], v177 offset:38912
	ds_read_b128 v[214:217], v177 offset:39936
	global_load_lds_dwordx4 v152, s[38:39]
	s_mov_b32 m0, s51
	s_nop 0
	global_load_lds_dwordx4 v154, s[38:39]
	s_waitcnt vmcnt(8)
	s_waitcnt lgkmcnt(0)
	s_setprio 1
	s_barrier
	v_mfma_f32_16x16x32_bf16 v[124:127], v[128:131], v[186:189], v[124:127]
	v_mfma_f32_16x16x32_bf16 v[120:123], v[136:139], v[186:189], v[120:123]
	v_mfma_f32_16x16x32_bf16 v[112:115], v[128:131], v[194:197], v[112:115]
	v_mfma_f32_16x16x32_bf16 v[116:119], v[136:139], v[194:197], v[116:119]
	v_mfma_f32_16x16x32_bf16 v[96:99], v[128:131], v[202:205], v[96:99]
	v_mfma_f32_16x16x32_bf16 v[104:107], v[136:139], v[202:205], v[104:107]
	v_mfma_f32_16x16x32_bf16 v[76:79], v[128:131], v[210:213], v[76:79]
	v_mfma_f32_16x16x32_bf16 v[72:75], v[136:139], v[210:213], v[72:75]
	v_mfma_f32_16x16x32_bf16 v[124:127], v[132:135], v[190:193], v[124:127]
	v_mfma_f32_16x16x32_bf16 v[120:123], v[140:143], v[190:193], v[120:123]
	v_mfma_f32_16x16x32_bf16 v[112:115], v[132:135], v[198:201], v[112:115]
	v_mfma_f32_16x16x32_bf16 v[116:119], v[140:143], v[198:201], v[116:119]
	v_mfma_f32_16x16x32_bf16 v[96:99], v[132:135], v[206:209], v[96:99]
	v_mfma_f32_16x16x32_bf16 v[104:107], v[140:143], v[206:209], v[104:107]
	v_mfma_f32_16x16x32_bf16 v[76:79], v[132:135], v[214:217], v[76:79]
	v_mfma_f32_16x16x32_bf16 v[72:75], v[140:143], v[214:217], v[72:75]
	v_mfma_f32_16x16x32_bf16 v[108:111], v[144:147], v[186:189], v[108:111]
	v_mfma_f32_16x16x32_bf16 v[100:103], v[168:171], v[186:189], v[100:103]
	v_mfma_f32_16x16x32_bf16 v[88:91], v[144:147], v[194:197], v[88:91]
	v_mfma_f32_16x16x32_bf16 v[92:95], v[168:171], v[194:197], v[92:95]
	v_mfma_f32_16x16x32_bf16 v[84:87], v[144:147], v[202:205], v[84:87]
	v_mfma_f32_16x16x32_bf16 v[80:83], v[168:171], v[202:205], v[80:83]
	v_mfma_f32_16x16x32_bf16 v[68:71], v[144:147], v[210:213], v[68:71]
	v_mfma_f32_16x16x32_bf16 v[64:67], v[168:171], v[210:213], v[64:67]
	v_mfma_f32_16x16x32_bf16 v[108:111], v[148:151], v[190:193], v[108:111]
	v_mfma_f32_16x16x32_bf16 v[100:103], v[182:185], v[190:193], v[100:103]
	v_mfma_f32_16x16x32_bf16 v[88:91], v[148:151], v[198:201], v[88:91]
	v_mfma_f32_16x16x32_bf16 v[92:95], v[182:185], v[198:201], v[92:95]
	v_mfma_f32_16x16x32_bf16 v[84:87], v[148:151], v[206:209], v[84:87]
	v_mfma_f32_16x16x32_bf16 v[80:83], v[182:185], v[206:209], v[80:83]
	v_mfma_f32_16x16x32_bf16 v[68:71], v[148:151], v[214:217], v[68:71]
	v_mfma_f32_16x16x32_bf16 v[64:67], v[182:185], v[214:217], v[64:67]
	s_barrier
	s_setprio 0
	s_add_i32 s38, s43, s47
	s_mov_b32 m0, s38
	ds_read_b128 v[186:189], v177 offset:49152
	ds_read_b128 v[190:193], v177 offset:50176
	ds_read_b128 v[194:197], v177 offset:51200
	ds_read_b128 v[198:201], v177 offset:52224
	ds_read_b128 v[202:205], v177 offset:53248
	ds_read_b128 v[206:209], v177 offset:54272
	ds_read_b128 v[210:213], v177 offset:55296
	ds_read_b128 v[214:217], v177 offset:56320
	global_load_lds_dwordx4 v152, s[98:99]
	s_add_i32 m0, s38, 0x2000
	s_add_u32 s36, s36, 0x20080
	s_addc_u32 s37, s37, 0
	s_add_i32 s38, s88, s47
	global_load_lds_dwordx4 v154, s[98:99]
	s_mov_b32 m0, s38
	s_nop 0
	global_load_lds_dwordx4 v152, s[36:37]
	s_add_i32 m0, s38, 0x2000
	s_nop 0
	global_load_lds_dwordx4 v154, s[36:37]
	s_mov_b32 m0, s61
	s_nop 0
	global_load_lds_dwordx4 v152, s[100:101]
	s_mov_b32 m0, s62
	s_nop 0
	global_load_lds_dwordx4 v154, s[100:101]
	s_waitcnt vmcnt(8)
	s_waitcnt lgkmcnt(0)
	s_setprio 1
	s_barrier
	v_mfma_f32_16x16x32_bf16 v[60:63], v[128:131], v[186:189], v[60:63]
	v_mfma_f32_16x16x32_bf16 v[56:59], v[136:139], v[186:189], v[56:59]
	v_mfma_f32_16x16x32_bf16 v[44:47], v[128:131], v[194:197], v[44:47]
	v_mfma_f32_16x16x32_bf16 v[40:43], v[136:139], v[194:197], v[40:43]
	v_mfma_f32_16x16x32_bf16 v[28:31], v[128:131], v[202:205], v[28:31]
	v_mfma_f32_16x16x32_bf16 v[24:27], v[136:139], v[202:205], v[24:27]
	v_mfma_f32_16x16x32_bf16 v[12:15], v[128:131], v[210:213], v[12:15]
	v_mfma_f32_16x16x32_bf16 v[8:11], v[136:139], v[210:213], v[8:11]
	v_mfma_f32_16x16x32_bf16 v[60:63], v[132:135], v[190:193], v[60:63]
	v_mfma_f32_16x16x32_bf16 v[56:59], v[140:143], v[190:193], v[56:59]
	v_mfma_f32_16x16x32_bf16 v[44:47], v[132:135], v[198:201], v[44:47]
	v_mfma_f32_16x16x32_bf16 v[40:43], v[140:143], v[198:201], v[40:43]
	v_mfma_f32_16x16x32_bf16 v[28:31], v[132:135], v[206:209], v[28:31]
	v_mfma_f32_16x16x32_bf16 v[24:27], v[140:143], v[206:209], v[24:27]
	v_mfma_f32_16x16x32_bf16 v[12:15], v[132:135], v[214:217], v[12:15]
	v_mfma_f32_16x16x32_bf16 v[8:11], v[140:143], v[214:217], v[8:11]
	v_mfma_f32_16x16x32_bf16 v[52:55], v[144:147], v[186:189], v[52:55]
	v_mfma_f32_16x16x32_bf16 v[48:51], v[168:171], v[186:189], v[48:51]
	v_mfma_f32_16x16x32_bf16 v[36:39], v[144:147], v[194:197], v[36:39]
	v_mfma_f32_16x16x32_bf16 v[32:35], v[168:171], v[194:197], v[32:35]
	v_mfma_f32_16x16x32_bf16 v[20:23], v[144:147], v[202:205], v[20:23]
	v_mfma_f32_16x16x32_bf16 v[16:19], v[168:171], v[202:205], v[16:19]
	v_mfma_f32_16x16x32_bf16 v[4:7], v[144:147], v[210:213], v[4:7]
	v_mfma_f32_16x16x32_bf16 v[0:3], v[168:171], v[210:213], v[0:3]
	v_mfma_f32_16x16x32_bf16 v[52:55], v[148:151], v[190:193], v[52:55]
	v_mfma_f32_16x16x32_bf16 v[48:51], v[182:185], v[190:193], v[48:51]
	v_mfma_f32_16x16x32_bf16 v[36:39], v[148:151], v[198:201], v[36:39]
	v_mfma_f32_16x16x32_bf16 v[32:35], v[182:185], v[198:201], v[32:35]
	v_mfma_f32_16x16x32_bf16 v[20:23], v[148:151], v[206:209], v[20:23]
	v_mfma_f32_16x16x32_bf16 v[16:19], v[182:185], v[206:209], v[16:19]
	v_mfma_f32_16x16x32_bf16 v[4:7], v[148:151], v[214:217], v[4:7]
	v_mfma_f32_16x16x32_bf16 v[0:3], v[182:185], v[214:217], v[0:3]
	s_barrier
	s_setprio 0
	s_add_i32 s42, s42, 2
	s_add_u32 s6, s6, 0x100
	s_addc_u32 s7, s7, 0
	s_add_u32 s40, s40, 0x100
	s_addc_u32 s41, s41, 0
	s_cmp_gt_u32 s42, 5
	s_cbranch_scc0 .LBB0_938
	s_and_b64 vcc, exec, s[18:19]
	s_cbranch_vccz .LBB0_941
	s_barrier
